# trim33 + two-accumulator row-sum + redundant wait cleanup + m0 hazard slot filled by the lgkmcnt wait (stacked micro-trims)
# baseline (speedup 1.0000x reference)
.Latt_head:
	s_lshl_b32 s14, s14, 1
	v_add_u32_e32 v217, s14, v244
	ds_read_b64_tr_b16 v[208:209], v217 offset:24576
	ds_read_b64_tr_b16 v[210:211], v217 offset:25088
	v_add_f32_e32 v224, v96, v97
	v_add_f32_e32 v225, v98, v99
	v_add_f32_e32 v224, v100, v224
	v_add_f32_e32 v225, v101, v225
	v_cvt_pk_bf16_f32 v164, v96, v97
	v_cvt_pk_bf16_f32 v165, v98, v99
	ds_read_b64_tr_b16 v[96:97], v217 offset:28672
	ds_read_b64_tr_b16 v[98:99], v217 offset:29184
	v_add_f32_e32 v224, v102, v224
	v_add_f32_e32 v225, v103, v225
	v_add_f32_e32 v224, v104, v224
	v_add_f32_e32 v225, v105, v225
	v_mfma_f32_32x32x16_bf16 v[112:127], v[200:203], v[172:175], v[64:79]
	v_cvt_pk_bf16_f32 v166, v100, v101
	v_cvt_pk_bf16_f32 v167, v102, v103
	ds_read_b64_tr_b16 v[100:101], v217 offset:25600
	ds_read_b64_tr_b16 v[102:103], v217 offset:26112
	v_mfma_f32_32x32x16_bf16 v[128:143], v[196:199], v[168:171], v[128:143]
	v_add_f32_e32 v224, v106, v224
	v_add_f32_e32 v225, v107, v225
	v_add_f32_e32 v224, v108, v224
	v_add_f32_e32 v225, v109, v225
	v_cvt_pk_bf16_f32 v156, v104, v105
	v_cvt_pk_bf16_f32 v157, v106, v107
	ds_read_b64_tr_b16 v[104:105], v217 offset:29696
	ds_read_b64_tr_b16 v[106:107], v217 offset:30208
	v_mfma_f32_32x32x16_bf16 v[112:127], v[192:195], v[168:171], v[112:127]
	v_add_f32_e32 v224, v110, v224
	v_add_f32_e32 v225, v111, v225
	v_add_f32_e32 v224, v80, v224
	v_add_f32_e32 v225, v81, v225
	v_cvt_pk_bf16_f32 v158, v108, v109
	v_cvt_pk_bf16_f32 v159, v110, v111
	ds_read_b64_tr_b16 v[108:109], v217 offset:26624
	ds_read_b64_tr_b16 v[110:111], v217 offset:27136
	v_mfma_f32_32x32x16_bf16 v[128:143], v[188:191], v[160:163], v[128:143]
	v_add_f32_e32 v224, v82, v224
	v_add_f32_e32 v225, v83, v225
	v_add_f32_e32 v224, v84, v224
	v_add_f32_e32 v225, v85, v225
	v_cvt_pk_bf16_f32 v148, v80, v81
	v_cvt_pk_bf16_f32 v149, v82, v83
	ds_read_b64_tr_b16 v[80:81], v217 offset:30720
	ds_read_b64_tr_b16 v[82:83], v217 offset:31232
	v_mfma_f32_32x32x16_bf16 v[112:127], v[184:187], v[160:163], v[112:127]
	v_add_f32_e32 v224, v86, v224
	v_add_f32_e32 v225, v87, v225
	v_add_f32_e32 v224, v88, v224
	v_add_f32_e32 v225, v89, v225
	v_cvt_pk_bf16_f32 v150, v84, v85
	v_cvt_pk_bf16_f32 v151, v86, v87
	ds_read_b64_tr_b16 v[84:85], v217 offset:27648
	ds_read_b64_tr_b16 v[86:87], v217 offset:28160
	v_mfma_f32_32x32x16_bf16 v[128:143], v[180:183], v[152:155], v[128:143]
	v_add_f32_e32 v224, v90, v224
	v_add_f32_e32 v225, v91, v225
	v_add_f32_e32 v224, v92, v224
	v_add_f32_e32 v225, v93, v225
	v_cvt_pk_bf16_f32 v144, v88, v89
	v_cvt_pk_bf16_f32 v145, v90, v91
	ds_read_b64_tr_b16 v[88:89], v217 offset:31744
	ds_read_b64_tr_b16 v[90:91], v217 offset:32256
	v_mfma_f32_32x32x16_bf16 v[112:127], v[176:179], v[152:155], v[112:127]
	v_add_f32_e32 v224, v94, v224
	v_add_f32_e32 v225, v95, v225
	v_add_f32_e32 v176, v224, v225
	v_cvt_pk_bf16_f32 v146, v92, v93
	v_cvt_pk_bf16_f32 v147, v94, v95
	s_add_i32 m0, s24, s63
	s_mov_b32 s14, s32
	s_mov_b32 s15, s70
	global_load_lds_dwordx4 v212, s[14:15]
	s_lshl_b32 s14, s22, 1
	s_add_i32 s14, s14, s64
	s_mov_b32 m0, s14
	s_add_i32 s14, s14, 0x1f80
	global_load_lds_dwordx4 v226, s[98:99]
	s_mov_b32 m0, s14
	s_waitcnt lgkmcnt(12)
	global_load_lds_dwordx4 v226, s[98:99] offset:128
	v_mfma_f32_32x32x16_bf16 v[32:47], v[164:167], v[208:211], v[32:47]
	v_max_f32_e32 v222, v128, v129
	v_max3_f32 v223, v130, v131, v113
	v_max3_f32 v222, v222, v112, v114
	v_max3_f32 v222, v222, v115, v132
	ds_read_b64_tr_b16 v[92:93], v217 offset:32768
	ds_read_b64_tr_b16 v[94:95], v217 offset:33280
	v_mfma_f32_32x32x16_bf16 v[48:63], v[164:167], v[96:99], v[48:63]
	v_max3_f32 v223, v223, v134, v135
	v_max3_f32 v222, v222, v133, v116
	v_max3_f32 v223, v223, v118, v119
	v_max3_f32 v222, v222, v117, v136
	ds_read_b64_tr_b16 v[96:97], v217 offset:36864
	ds_read_b64_tr_b16 v[98:99], v217 offset:37376
	s_waitcnt lgkmcnt(12)
	v_mfma_f32_32x32x16_bf16 v[32:47], v[156:159], v[100:103], v[32:47]
	v_max3_f32 v223, v223, v138, v139
	v_max3_f32 v222, v222, v137, v120
	v_max3_f32 v223, v223, v122, v123
	v_max3_f32 v222, v222, v121, v140
	ds_read_b64_tr_b16 v[100:101], v217 offset:33792
	ds_read_b64_tr_b16 v[102:103], v217 offset:34304
	v_mfma_f32_32x32x16_bf16 v[48:63], v[156:159], v[104:107], v[48:63]
	v_max3_f32 v223, v223, v142, v143
	v_max3_f32 v222, v222, v141, v124
	v_max3_f32 v223, v223, v126, v127
	v_max3_f32 v222, v222, v125, v223
	ds_read_b64_tr_b16 v[104:105], v217 offset:37888
	ds_read_b64_tr_b16 v[106:107], v217 offset:38400
	s_waitcnt lgkmcnt(12)
	v_mfma_f32_32x32x16_bf16 v[32:47], v[148:151], v[108:111], v[32:47]
	v_mov_b32_e32 v223, v222
	v_add_f32_e32 v215, v249, v176
	s_nop 0
	v_permlane32_swap_b32_e32 v222, v223
	v_max_f32_e32 v222, v222, v223
	v_cmp_lt_f32_e32 vcc, s33, v222
	s_nop 0
	s_mov_b64 s[20:21], vcc
	s_cbranch_vccnz .LBB0_318

.LBB0_313:
	v_mfma_f32_32x32x16_bf16 v[96:111], v[80:83], v[172:175], v[64:79]
	s_add_i32 s14, s22, 0x2000
	s_cmpk_lg_i32 s22, 0x4000
	s_cselect_b32 s66, s14, 0
	s_lshl_b32 s14, s24, 1
	v_add_u32_e32 v209, s14, v244
	ds_read_b64_tr_b16 v[188:189], v209 offset:24576
	ds_read_b64_tr_b16 v[190:191], v209 offset:25088
	v_add_f32_e32 v222, v128, v129
	v_add_f32_e32 v223, v130, v131
	v_add_f32_e32 v222, v132, v222
	v_add_f32_e32 v223, v133, v223
	v_cvt_pk_bf16_f32 v164, v128, v129
	v_cvt_pk_bf16_f32 v165, v130, v131
	ds_read_b64_tr_b16 v[128:129], v209 offset:28672
	ds_read_b64_tr_b16 v[130:131], v209 offset:29184
	v_add_f32_e32 v222, v134, v222
	v_add_f32_e32 v223, v135, v223
	v_add_f32_e32 v222, v136, v222
	v_add_f32_e32 v223, v137, v223
	v_mfma_f32_32x32x16_bf16 v[80:95], v[200:203], v[172:175], v[64:79]
	v_cvt_pk_bf16_f32 v166, v132, v133
	v_cvt_pk_bf16_f32 v167, v134, v135
	ds_read_b64_tr_b16 v[132:133], v209 offset:25600
	ds_read_b64_tr_b16 v[134:135], v209 offset:26112
	v_mfma_f32_32x32x16_bf16 v[96:111], v[204:207], v[168:171], v[96:111]
	v_add_f32_e32 v222, v138, v222
	v_add_f32_e32 v223, v139, v223
	v_add_f32_e32 v222, v140, v222
	v_add_f32_e32 v223, v141, v223
	v_cvt_pk_bf16_f32 v156, v136, v137
	v_cvt_pk_bf16_f32 v157, v138, v139
	ds_read_b64_tr_b16 v[136:137], v209 offset:29696
	ds_read_b64_tr_b16 v[138:139], v209 offset:30208
	v_mfma_f32_32x32x16_bf16 v[80:95], v[196:199], v[168:171], v[80:95]
	v_add_f32_e32 v222, v142, v222
	v_add_f32_e32 v223, v143, v223
	v_add_f32_e32 v222, v112, v222
	v_add_f32_e32 v223, v113, v223
	v_cvt_pk_bf16_f32 v158, v140, v141
	v_cvt_pk_bf16_f32 v159, v142, v143
	ds_read_b64_tr_b16 v[140:141], v209 offset:26624
	ds_read_b64_tr_b16 v[142:143], v209 offset:27136
	v_mfma_f32_32x32x16_bf16 v[96:111], v[192:195], v[160:163], v[96:111]
	v_add_f32_e32 v222, v114, v222
	v_add_f32_e32 v223, v115, v223
	v_add_f32_e32 v222, v116, v222
	v_add_f32_e32 v223, v117, v223
	v_cvt_pk_bf16_f32 v148, v112, v113
	v_cvt_pk_bf16_f32 v149, v114, v115
	ds_read_b64_tr_b16 v[112:113], v209 offset:30720
	ds_read_b64_tr_b16 v[114:115], v209 offset:31232
	v_mfma_f32_32x32x16_bf16 v[80:95], v[184:187], v[160:163], v[80:95]
	v_add_f32_e32 v222, v118, v222
	v_add_f32_e32 v223, v119, v223
	v_add_f32_e32 v222, v120, v222
	v_add_f32_e32 v223, v121, v223
	v_cvt_pk_bf16_f32 v150, v116, v117
	v_cvt_pk_bf16_f32 v151, v118, v119
	ds_read_b64_tr_b16 v[116:117], v209 offset:27648
	ds_read_b64_tr_b16 v[118:119], v209 offset:28160
	v_mfma_f32_32x32x16_bf16 v[96:111], v[180:183], v[152:155], v[96:111]
	v_add_f32_e32 v222, v122, v222
	v_add_f32_e32 v223, v123, v223
	v_add_f32_e32 v222, v124, v222
	v_add_f32_e32 v223, v125, v223
	v_cvt_pk_bf16_f32 v144, v120, v121
	v_cvt_pk_bf16_f32 v145, v122, v123
	ds_read_b64_tr_b16 v[120:121], v209 offset:31744
	ds_read_b64_tr_b16 v[122:123], v209 offset:32256
	v_mfma_f32_32x32x16_bf16 v[80:95], v[176:179], v[152:155], v[80:95]
	v_add_f32_e32 v222, v126, v222
	v_add_f32_e32 v223, v127, v223
	v_add_f32_e32 v176, v222, v223
	v_cvt_pk_bf16_f32 v146, v124, v125
	v_cvt_pk_bf16_f32 v147, v126, v127
	s_add_i32 m0, s22, s63
	s_add_u32 s14, s32, 0x20000
	s_addc_u32 s15, s70, 0
	global_load_lds_dwordx4 v212, s[14:15]
	s_lshl_b32 s20, s66, 1
	s_add_i32 s20, s20, s64
	s_add_u32 s14, s98, 0x20000
	s_addc_u32 s15, s99, 0
	s_mov_b32 m0, s20
	s_add_i32 s20, s20, 0x1f80
	global_load_lds_dwordx4 v226, s[14:15]
	s_mov_b32 m0, s20
	s_waitcnt lgkmcnt(12)
	global_load_lds_dwordx4 v226, s[14:15] offset:128
	v_mfma_f32_32x32x16_bf16 v[32:47], v[164:167], v[188:191], v[32:47]
	v_max_f32_e32 v224, v96, v97
	v_max3_f32 v225, v98, v99, v81
	v_max3_f32 v224, v224, v80, v82
	v_max3_f32 v224, v224, v83, v100
	ds_read_b64_tr_b16 v[124:125], v209 offset:32768
	ds_read_b64_tr_b16 v[126:127], v209 offset:33280
	v_mfma_f32_32x32x16_bf16 v[48:63], v[164:167], v[128:131], v[48:63]
	v_max3_f32 v225, v225, v102, v103
	v_max3_f32 v224, v224, v101, v84
	v_max3_f32 v225, v225, v86, v87
	v_max3_f32 v224, v224, v85, v104
	ds_read_b64_tr_b16 v[128:129], v209 offset:36864
	ds_read_b64_tr_b16 v[130:131], v209 offset:37376
	s_waitcnt lgkmcnt(12)
	v_mfma_f32_32x32x16_bf16 v[32:47], v[156:159], v[132:135], v[32:47]
	v_max3_f32 v225, v225, v106, v107
	v_max3_f32 v224, v224, v105, v88
	v_max3_f32 v225, v225, v90, v91
	v_max3_f32 v224, v224, v89, v108
	ds_read_b64_tr_b16 v[132:133], v209 offset:33792
	ds_read_b64_tr_b16 v[134:135], v209 offset:34304
	v_mfma_f32_32x32x16_bf16 v[48:63], v[156:159], v[136:139], v[48:63]
	v_max3_f32 v225, v225, v110, v111
	v_max3_f32 v224, v224, v109, v92
	v_max3_f32 v225, v225, v94, v95
	v_max3_f32 v224, v224, v93, v225
	ds_read_b64_tr_b16 v[136:137], v209 offset:37888
	ds_read_b64_tr_b16 v[138:139], v209 offset:38400
	s_waitcnt lgkmcnt(12)
	v_mfma_f32_32x32x16_bf16 v[32:47], v[148:151], v[140:143], v[32:47]
	v_mov_b32_e32 v225, v224
	v_add_f32_e32 v249, v215, v176
	s_nop 0
	v_permlane32_swap_b32_e32 v224, v225
	v_max_f32_e32 v224, v224, v225
	v_cmp_lt_f32_e32 vcc, s33, v224
	s_nop 0
	s_mov_b64 s[20:21], vcc
	s_cbranch_vccnz .LBB0_321
